# lru row prefetch on sample tiles: conv-state loads of three row blocks issued together, one wait per batch (6 exposed latencies -> 2)
# speedup vs baseline: 1.0107x; 1.0107x over previous
; #define LAS __attribute__((address_space(3)))
; __device__ __forceinline__ float bflo(unsigned w) { return __uint_as_float(w << 16); }
; __device__ __forceinline__ float bfhi(unsigned w) { return __uint_as_float(w & 0xffff0000u); }
; __device__ __forceinline__ u32x4 pack8(f32x4 a, f32x4 b) { u32x4 w; w.x = cvtpk(a[0], a[1]); w.y = cvtpk(a[2], a[3]); w.z = cvtpk(b[0], b[1]); w.w = cvtpk(b[2], b[3]); return w; }
; __device__ __forceinline__ void lru_load_rows(const Params& P, int l, int tile, int r0, int c0, u32x4 (&xr)[2][4]) {
;     const bf16* XR = (const bf16*)(P.ws + WS_XR);
;     const bool samp = tile * 64 >= NPT;
; #pragma unroll
;     for (int j = 0; j < 2; ++j) {
;         const int m = tile * 64 + r0 + 32 * j;
;         const int pos = samp ? ((m - NPT) & 3) : (m % LP);
; #pragma unroll
;         for (int i = 0; i < 4; ++i) {
;             u32x4 v = {0u, 0u, 0u, 0u};
;             if (pos - i >= 0) v = *(const u32x4*)(XR + (size_t)(m - i) * 1024 + c0);
; template <int MODE> __device__ __forceinline__ void lru_phase(const Params& P, LAS unsigned char* lds, int l, int tid_in) {
;     ...
; #pragma unroll
;             for (int j = 0; j < 2; ++j) {
;                 f32x4 a0 = *(const LAS f32x4*)(cwl + 512 + c8 * 8), a1 = *(const LAS f32x4*)(cwl + 512 + c8 * 8 + 4);
; #pragma unroll
;                 for (int i = 0; i < 4; ++i) { const u32x4 xw = xr[j][i]; f32x4 x0, x1; const f32x4 w0 = *(const LAS f32x4*)(cwl + i * 128 + c8 * 8), w1 = *(const LAS f32x4*)(cwl + i * 128 + c8 * 8 + 4);
;                     x0[0] = bflo(xw.x); x0[1] = bfhi(xw.x); x0[2] = bflo(xw.y); x0[3] = bfhi(xw.y); x1[0] = bflo(xw.z); x1[1] = bfhi(xw.z); x1[2] = bflo(xw.w); x1[3] = bfhi(xw.w);
;                     a0 += w0 * x0; a1 += w1 * x1; }
;                 *(LAS u32x4*)(xcb + (r0 + 32 * j) * 136 + c8 * 8) = pack8(a0, a1);
;             }
;             if (tile + tstride < NTILE64) lru_load_rows(P, l, tile + tstride, r0, c0, xr);
.LBB0_1105:
	s_cmpk_lt_u32 s42, 0x10a
	s_cselect_b64 s[4:5], -1, 0
	s_cmp_gt_i32 s12, -1
	s_cselect_b64 s[54:55], -1, 0
	s_or_b64 s[0:1], s[54:55], s[4:5]
	v_cndmask_b32_e64 v0, 0, 1, s[0:1]
	v_cmp_ne_u32_e64 s[46:47], 1, v0
	s_andn2_b64 vcc, exec, s[0:1]
	s_cbranch_vccnz .LBB0_1113
	v_cndmask_b32_e64 v0, 0, 1, s[4:5]
	v_cmp_ne_u32_e64 s[48:49], 1, v0
	s_andn2_b64 vcc, exec, s[4:5]
	s_lshl_b32 s43, s42, 6
	s_cbranch_vccnz .LBB0_1159
	ds_read_b128 v[0:3], v182
	ds_read_b128 v[4:7], v182 offset:16
	ds_read_b128 v[8:11], v183
	ds_read_b128 v[12:15], v183 offset:16
	ds_read_b128 v[24:27], v183 offset:512
	ds_read_b128 v[28:31], v183 offset:528
	s_waitcnt vmcnt(2)
	v_lshlrev_b32_e32 v16, 16, v120
	v_and_b32_e32 v17, 0xffff0000, v120
	v_lshlrev_b32_e32 v18, 16, v121
	v_and_b32_e32 v19, 0xffff0000, v121
	v_lshlrev_b32_e32 v20, 16, v122
	v_and_b32_e32 v21, 0xffff0000, v122
	v_lshlrev_b32_e32 v22, 16, v123
	v_and_b32_e32 v23, 0xffff0000, v123
	s_waitcnt lgkmcnt(2)
	v_pk_fma_f32 v[8:9], v[8:9], v[16:17], v[0:1]
	v_pk_fma_f32 v[10:11], v[10:11], v[18:19], v[2:3]
	v_pk_fma_f32 v[12:13], v[12:13], v[20:21], v[4:5]
	v_pk_fma_f32 v[14:15], v[14:15], v[22:23], v[6:7]
	ds_read_b128 v[0:3], v183 offset:1024
	ds_read_b128 v[4:7], v183 offset:1040
	v_lshlrev_b32_e32 v16, 16, v124
	v_and_b32_e32 v17, 0xffff0000, v124
	v_lshlrev_b32_e32 v18, 16, v125
	v_and_b32_e32 v19, 0xffff0000, v125
	v_lshlrev_b32_e32 v20, 16, v126
	v_and_b32_e32 v21, 0xffff0000, v126
	v_lshlrev_b32_e32 v22, 16, v127
	v_and_b32_e32 v23, 0xffff0000, v127
	s_waitcnt lgkmcnt(2)
	v_pk_fma_f32 v[10:11], v[26:27], v[18:19], v[10:11]
	v_pk_fma_f32 v[8:9], v[24:25], v[16:17], v[8:9]
	v_pk_fma_f32 v[14:15], v[30:31], v[22:23], v[14:15]
	v_pk_fma_f32 v[12:13], v[28:29], v[20:21], v[12:13]
	ds_read_b128 v[24:27], v183 offset:1536
	ds_read_b128 v[28:31], v183 offset:1552
	v_lshlrev_b32_e32 v16, 16, v128
	v_and_b32_e32 v17, 0xffff0000, v128
	v_lshlrev_b32_e32 v18, 16, v129
	v_and_b32_e32 v19, 0xffff0000, v129
	v_lshlrev_b32_e32 v20, 16, v130
	v_and_b32_e32 v21, 0xffff0000, v130
	v_lshlrev_b32_e32 v22, 16, v131
	v_and_b32_e32 v23, 0xffff0000, v131
	s_waitcnt lgkmcnt(2)
	v_pk_fma_f32 v[8:9], v[0:1], v[16:17], v[8:9]
	v_pk_fma_f32 v[10:11], v[2:3], v[18:19], v[10:11]
	v_pk_fma_f32 v[12:13], v[4:5], v[20:21], v[12:13]
	v_pk_fma_f32 v[14:15], v[6:7], v[22:23], v[14:15]
	v_lshlrev_b32_e32 v16, 16, v132
	v_and_b32_e32 v17, 0xffff0000, v132
	v_lshlrev_b32_e32 v18, 16, v133
	v_and_b32_e32 v19, 0xffff0000, v133
	v_lshlrev_b32_e32 v20, 16, v134
	v_and_b32_e32 v21, 0xffff0000, v134
	v_lshlrev_b32_e32 v22, 16, v135
	v_and_b32_e32 v23, 0xffff0000, v135
	s_waitcnt lgkmcnt(0)
	v_pk_fma_f32 v[2:3], v[26:27], v[18:19], v[10:11]
	v_pk_fma_f32 v[0:1], v[24:25], v[16:17], v[8:9]
	v_pk_fma_f32 v[6:7], v[30:31], v[22:23], v[14:15]
	v_pk_fma_f32 v[4:5], v[28:29], v[20:21], v[12:13]
	v_cvt_pk_bf16_f32 v0, v0, v1
	v_cvt_pk_bf16_f32 v1, v2, v3
	v_cvt_pk_bf16_f32 v2, v4, v5
	v_cvt_pk_bf16_f32 v3, v6, v7
	ds_write_b128 v238, v[0:3]
	ds_read_b128 v[0:3], v182
	ds_read_b128 v[4:7], v182 offset:16
	ds_read_b128 v[8:11], v183
	ds_read_b128 v[12:15], v183 offset:16
	ds_read_b128 v[24:27], v183 offset:512
	ds_read_b128 v[28:31], v183 offset:528
	v_lshlrev_b32_e32 v16, 16, v136
	v_and_b32_e32 v17, 0xffff0000, v136
	v_lshlrev_b32_e32 v18, 16, v137
	v_and_b32_e32 v19, 0xffff0000, v137
	v_lshlrev_b32_e32 v20, 16, v138
	v_and_b32_e32 v21, 0xffff0000, v138
	v_lshlrev_b32_e32 v22, 16, v139
	v_and_b32_e32 v23, 0xffff0000, v139
	s_waitcnt lgkmcnt(2)
	v_pk_fma_f32 v[8:9], v[8:9], v[16:17], v[0:1]
	v_pk_fma_f32 v[10:11], v[10:11], v[18:19], v[2:3]
	v_pk_fma_f32 v[12:13], v[12:13], v[20:21], v[4:5]
	v_pk_fma_f32 v[14:15], v[14:15], v[22:23], v[6:7]
	ds_read_b128 v[0:3], v183 offset:1024
	ds_read_b128 v[4:7], v183 offset:1040
	v_lshlrev_b32_e32 v16, 16, v140
	v_and_b32_e32 v17, 0xffff0000, v140
	v_lshlrev_b32_e32 v18, 16, v141
	v_and_b32_e32 v19, 0xffff0000, v141
	v_lshlrev_b32_e32 v20, 16, v142
	v_and_b32_e32 v21, 0xffff0000, v142
	v_lshlrev_b32_e32 v22, 16, v143
	v_and_b32_e32 v23, 0xffff0000, v143
	s_waitcnt lgkmcnt(2)
	v_pk_fma_f32 v[10:11], v[26:27], v[18:19], v[10:11]
	v_pk_fma_f32 v[8:9], v[24:25], v[16:17], v[8:9]
	v_pk_fma_f32 v[14:15], v[30:31], v[22:23], v[14:15]
	v_pk_fma_f32 v[12:13], v[28:29], v[20:21], v[12:13]
	ds_read_b128 v[24:27], v183 offset:1536
	ds_read_b128 v[28:31], v183 offset:1552
	v_lshlrev_b32_e32 v16, 16, v144
	v_and_b32_e32 v17, 0xffff0000, v144
	v_lshlrev_b32_e32 v18, 16, v145
	v_and_b32_e32 v19, 0xffff0000, v145
	v_lshlrev_b32_e32 v20, 16, v146
	v_and_b32_e32 v21, 0xffff0000, v146
	v_lshlrev_b32_e32 v22, 16, v147
	v_and_b32_e32 v23, 0xffff0000, v147
	s_waitcnt lgkmcnt(2)
	v_pk_fma_f32 v[8:9], v[0:1], v[16:17], v[8:9]
	v_pk_fma_f32 v[10:11], v[2:3], v[18:19], v[10:11]
	v_pk_fma_f32 v[12:13], v[4:5], v[20:21], v[12:13]
	v_pk_fma_f32 v[14:15], v[6:7], v[22:23], v[14:15]
	v_lshlrev_b32_e32 v16, 16, v148
	v_and_b32_e32 v17, 0xffff0000, v148
	v_lshlrev_b32_e32 v18, 16, v149
	v_and_b32_e32 v19, 0xffff0000, v149
	v_lshlrev_b32_e32 v20, 16, v150
	v_and_b32_e32 v21, 0xffff0000, v150
	v_lshlrev_b32_e32 v22, 16, v151
	v_and_b32_e32 v23, 0xffff0000, v151
	s_waitcnt lgkmcnt(0)
	v_pk_fma_f32 v[2:3], v[26:27], v[18:19], v[10:11]
	v_pk_fma_f32 v[0:1], v[24:25], v[16:17], v[8:9]
	v_pk_fma_f32 v[6:7], v[30:31], v[22:23], v[14:15]
	v_pk_fma_f32 v[4:5], v[28:29], v[20:21], v[12:13]
	v_cvt_pk_bf16_f32 v0, v0, v1
	v_cvt_pk_bf16_f32 v1, v2, v3
	v_cvt_pk_bf16_f32 v2, v4, v5
	v_cvt_pk_bf16_f32 v3, v6, v7
	v_readlane_b32 s0, v255, 32
	s_nop 0
	s_add_i32 s0, s42, s0
	s_cmpk_gt_u32 s0, 0x109
	ds_write_b128 v238, v[0:3] offset:8704
	s_cbranch_scc1 .LBB0_1158
	s_mov_b64 s[88:89], 0
	s_mov_b64 s[90:91], 0
	s_mov_b64 s[92:93], 0
	s_mov_b64 s[60:61], 0
	s_mov_b64 s[62:63], 0
	s_mov_b64 s[66:67], 0
	v_lshl_add_u32 v0, s0, 6, v177
	v_mul_hi_i32 v1, v0, s71
	v_lshrrev_b32_e32 v2, 31, v1
	v_ashrrev_i32_e32 v1, 7, v1
	v_add_u32_e32 v1, v1, v2
	s_cmpk_gt_u32 s0, 0x101
	v_mul_lo_u32 v1, v1, s73
	v_sub_u32_e32 v1, v0, v1
	s_cselect_b64 s[52:53], -1, 0
	v_cndmask_b32_e64 v4, v1, v154, s[52:53]
	v_cmp_lt_i32_e32 vcc, -1, v4
	v_ashrrev_i32_e32 v1, 31, v0
	s_and_saveexec_b64 s[0:1], vcc
	s_xor_b64 s[0:1], exec, s[0:1]
	s_cbranch_execz .LBB0_1110
	v_lshlrev_b64 v[2:3], 11, v[0:1]
	v_lshl_add_u64 v[2:3], v[168:169], 0, v[2:3]
	global_load_dwordx4 v[120:123], v[2:3], off

; __device__ __forceinline__ u32x4 pack8(f32x4 a, f32x4 b) { u32x4 w; w.x = cvtpk(a[0], a[1]); w.y = cvtpk(a[2], a[3]); w.z = cvtpk(b[0], b[1]); w.w = cvtpk(b[2], b[3]); return w; }
; __device__ __forceinline__ void lru_load_rows(const Params& P, int l, int tile, int r0, int c0, u32x4 (&xr)[2][4]) {
;     ...
;             if (pos - i >= 0) v = *(const u32x4*)(XR + (size_t)(m - i) * 1024 + c0);
;             else if (samp) { const float* buf = P.in[I_SC] + ((size_t)((l * 128 + ((m - NPT) >> 2)) * 3) + (3 + pos - i)) * 1024 + c0; v = pack8(*(const f32x4*)buf, *(const f32x4*)(buf + 4)); }
.LBB0_1117:
	s_andn2_saveexec_b64 s[0:1], s[0:1]
	s_cbranch_execz .LBB0_1121
	s_and_b64 vcc, exec, s[50:51]
	s_cbranch_vccnz .LBB0_1120
	s_mov_b64 s[88:89], exec
	v_lshl_add_u64 v[6:7], v[2:3], 0, v[160:161]
	v_lshlrev_b64 v[6:7], 12, v[6:7]
	v_lshl_add_u64 v[10:11], v[166:167], 0, v[6:7]
	global_load_dwordx4 v[20:23], v[10:11], off
	global_load_dwordx4 v[24:27], v[10:11], off offset:16
	s_branch .LBB0_1121

; __device__ __forceinline__ u32x4 pack8(f32x4 a, f32x4 b) { u32x4 w; w.x = cvtpk(a[0], a[1]); w.y = cvtpk(a[2], a[3]); w.z = cvtpk(b[0], b[1]); w.w = cvtpk(b[2], b[3]); return w; }
; __device__ __forceinline__ void lru_load_rows(const Params& P, int l, int tile, int r0, int c0, u32x4 (&xr)[2][4]) {
;     ...
;             if (pos - i >= 0) v = *(const u32x4*)(XR + (size_t)(m - i) * 1024 + c0);
;             else if (samp) { const float* buf = P.in[I_SC] + ((size_t)((l * 128 + ((m - NPT) >> 2)) * 3) + (3 + pos - i)) * 1024 + c0; v = pack8(*(const f32x4*)buf, *(const f32x4*)(buf + 4)); }
.LBB0_1123:
	s_andn2_saveexec_b64 s[0:1], s[0:1]
	s_cbranch_execz .LBB0_1127
	s_and_b64 vcc, exec, s[50:51]
	s_cbranch_vccnz .LBB0_1126
	s_mov_b64 s[90:91], exec
	v_lshl_add_u64 v[6:7], v[2:3], 0, v[162:163]
	v_lshlrev_b64 v[6:7], 12, v[6:7]
	v_lshl_add_u64 v[10:11], v[166:167], 0, v[6:7]
	global_load_dwordx4 v[28:31], v[10:11], off
	global_load_dwordx4 v[82:85], v[10:11], off offset:16
	s_branch .LBB0_1127

; __device__ __forceinline__ u32x4 pack8(f32x4 a, f32x4 b) { u32x4 w; w.x = cvtpk(a[0], a[1]); w.y = cvtpk(a[2], a[3]); w.z = cvtpk(b[0], b[1]); w.w = cvtpk(b[2], b[3]); return w; }
; __device__ __forceinline__ void lru_load_rows(const Params& P, int l, int tile, int r0, int c0, u32x4 (&xr)[2][4]) {
;     ...
;             if (pos - i >= 0) v = *(const u32x4*)(XR + (size_t)(m - i) * 1024 + c0);
;             else if (samp) { const float* buf = P.in[I_SC] + ((size_t)((l * 128 + ((m - NPT) >> 2)) * 3) + (3 + pos - i)) * 1024 + c0; v = pack8(*(const f32x4*)buf, *(const f32x4*)(buf + 4)); }
.LBB0_1129:
	s_andn2_saveexec_b64 s[0:1], s[0:1]
	s_cbranch_execz .LBB0_1133
	s_and_b64 vcc, exec, s[50:51]
	s_cbranch_vccnz .LBB0_1132
	s_mov_b64 s[92:93], exec
	v_lshl_add_u64 v[2:3], v[2:3], 0, v[154:155]
	v_lshlrev_b64 v[2:3], 12, v[2:3]
	v_lshl_add_u64 v[6:7], v[166:167], 0, v[2:3]
	global_load_dwordx4 v[186:189], v[6:7], off
	global_load_dwordx4 v[226:229], v[6:7], off offset:16
	s_branch .LBB0_1133

; __device__ __forceinline__ u32x4 pack8(f32x4 a, f32x4 b) { u32x4 w; w.x = cvtpk(a[0], a[1]); w.y = cvtpk(a[2], a[3]); w.z = cvtpk(b[0], b[1]); w.w = cvtpk(b[2], b[3]); return w; }
; __device__ __forceinline__ void lru_load_rows(const Params& P, int l, int tile, int r0, int c0, u32x4 (&xr)[2][4]) {
;     const bf16* XR = (const bf16*)(P.ws + WS_XR);
;     const bool samp = tile * 64 >= NPT;
; #pragma unroll
;     for (int j = 0; j < 2; ++j) {
;         const int m = tile * 64 + r0 + 32 * j;
;         const int pos = samp ? ((m - NPT) & 3) : (m % LP);
; #pragma unroll
;         for (int i = 0; i < 4; ++i) {
;             u32x4 v = {0u, 0u, 0u, 0u};
;             if (pos - i >= 0) v = *(const u32x4*)(XR + (size_t)(m - i) * 1024 + c0);
;             else if (samp) { const float* buf = P.in[I_SC] + ((size_t)((l * 128 + ((m - NPT) >> 2)) * 3) + (3 + pos - i)) * 1024 + c0; v = pack8(*(const f32x4*)buf, *(const f32x4*)(buf + 4)); }
;             xr[j][i] = v;
.LBB0_1133:
	s_or_b64 exec, exec, s[0:1]
	s_or_b64 s[76:77], s[88:89], s[90:91]
	s_or_b64 s[76:77], s[76:77], s[92:93]
	s_cmp_eq_u64 s[76:77], 0
	s_cbranch_scc1 .Lpf_samp_donea
	s_mov_b64 s[74:75], exec
	s_waitcnt vmcnt(0)
	s_mov_b64 exec, s[88:89]
	v_cvt_pk_bf16_f32 v124, v20, v21
	v_cvt_pk_bf16_f32 v125, v22, v23
	v_cvt_pk_bf16_f32 v126, v24, v25
	v_cvt_pk_bf16_f32 v127, v26, v27
	s_mov_b64 exec, s[90:91]
	v_cvt_pk_bf16_f32 v128, v28, v29
	v_cvt_pk_bf16_f32 v129, v30, v31
	v_cvt_pk_bf16_f32 v130, v82, v83
	v_cvt_pk_bf16_f32 v131, v84, v85
	s_mov_b64 exec, s[92:93]
	v_cvt_pk_bf16_f32 v132, v186, v187
	v_cvt_pk_bf16_f32 v133, v188, v189
	v_cvt_pk_bf16_f32 v134, v226, v227
	v_cvt_pk_bf16_f32 v135, v228, v229
	s_mov_b64 exec, s[74:75]
.Lpf_samp_donea:
	v_add_u32_e32 v2, 32, v0
	v_mul_hi_i32 v3, v2, s71
	v_lshrrev_b32_e32 v4, 31, v3
	v_ashrrev_i32_e32 v3, 7, v3
	v_add_u32_e32 v3, v3, v4
	v_mul_lo_u32 v3, v3, s73
	v_sub_u32_e32 v3, v2, v3
	v_cndmask_b32_e64 v4, v3, v154, s[52:53]
	v_cmp_lt_i32_e32 vcc, -1, v4
	s_and_saveexec_b64 s[0:1], vcc
	s_xor_b64 s[0:1], exec, s[0:1]
	s_cbranch_execz .LBB0_1135
	v_ashrrev_i32_e32 v3, 31, v2
	v_lshlrev_b64 v[2:3], 11, v[2:3]
	v_lshl_add_u64 v[2:3], v[168:169], 0, v[2:3]
	global_load_dwordx4 v[136:139], v[2:3], off

; __device__ __forceinline__ u32x4 pack8(f32x4 a, f32x4 b) { u32x4 w; w.x = cvtpk(a[0], a[1]); w.y = cvtpk(a[2], a[3]); w.z = cvtpk(b[0], b[1]); w.w = cvtpk(b[2], b[3]); return w; }
; __device__ __forceinline__ void lru_load_rows(const Params& P, int l, int tile, int r0, int c0, u32x4 (&xr)[2][4]) {
;     ...
;             if (pos - i >= 0) v = *(const u32x4*)(XR + (size_t)(m - i) * 1024 + c0);
;             else if (samp) { const float* buf = P.in[I_SC] + ((size_t)((l * 128 + ((m - NPT) >> 2)) * 3) + (3 + pos - i)) * 1024 + c0; v = pack8(*(const f32x4*)buf, *(const f32x4*)(buf + 4)); }
.LBB0_1141:
	s_andn2_saveexec_b64 s[0:1], s[0:1]
	s_cbranch_execz .LBB0_1145
	s_and_b64 vcc, exec, s[50:51]
	s_cbranch_vccnz .LBB0_1144
	s_mov_b64 s[60:61], exec
	v_lshl_add_u64 v[6:7], v[2:3], 0, v[160:161]
	v_lshlrev_b64 v[6:7], 12, v[6:7]
	v_lshl_add_u64 v[10:11], v[166:167], 0, v[6:7]
	global_load_dwordx4 v[20:23], v[10:11], off
	global_load_dwordx4 v[24:27], v[10:11], off offset:16
	s_branch .LBB0_1145

; __device__ __forceinline__ u32x4 pack8(f32x4 a, f32x4 b) { u32x4 w; w.x = cvtpk(a[0], a[1]); w.y = cvtpk(a[2], a[3]); w.z = cvtpk(b[0], b[1]); w.w = cvtpk(b[2], b[3]); return w; }
; __device__ __forceinline__ void lru_load_rows(const Params& P, int l, int tile, int r0, int c0, u32x4 (&xr)[2][4]) {
;     ...
;             if (pos - i >= 0) v = *(const u32x4*)(XR + (size_t)(m - i) * 1024 + c0);
;             else if (samp) { const float* buf = P.in[I_SC] + ((size_t)((l * 128 + ((m - NPT) >> 2)) * 3) + (3 + pos - i)) * 1024 + c0; v = pack8(*(const f32x4*)buf, *(const f32x4*)(buf + 4)); }
.LBB0_1147:
	s_andn2_saveexec_b64 s[0:1], s[0:1]
	s_cbranch_execz .LBB0_1151
	s_and_b64 vcc, exec, s[50:51]
	s_cbranch_vccnz .LBB0_1150
	s_mov_b64 s[62:63], exec
	v_lshl_add_u64 v[6:7], v[2:3], 0, v[162:163]
	v_lshlrev_b64 v[6:7], 12, v[6:7]
	v_lshl_add_u64 v[10:11], v[166:167], 0, v[6:7]
	global_load_dwordx4 v[28:31], v[10:11], off
	global_load_dwordx4 v[82:85], v[10:11], off offset:16
	s_branch .LBB0_1151

; __device__ __forceinline__ u32x4 pack8(f32x4 a, f32x4 b) { u32x4 w; w.x = cvtpk(a[0], a[1]); w.y = cvtpk(a[2], a[3]); w.z = cvtpk(b[0], b[1]); w.w = cvtpk(b[2], b[3]); return w; }
; __device__ __forceinline__ void lru_load_rows(const Params& P, int l, int tile, int r0, int c0, u32x4 (&xr)[2][4]) {
;     ...
;             if (pos - i >= 0) v = *(const u32x4*)(XR + (size_t)(m - i) * 1024 + c0);
;             else if (samp) { const float* buf = P.in[I_SC] + ((size_t)((l * 128 + ((m - NPT) >> 2)) * 3) + (3 + pos - i)) * 1024 + c0; v = pack8(*(const f32x4*)buf, *(const f32x4*)(buf + 4)); }
.LBB0_1153:
	s_andn2_saveexec_b64 s[0:1], s[0:1]
	s_cbranch_execz .LBB0_1157
	s_and_b64 vcc, exec, s[50:51]
	s_cbranch_vccnz .LBB0_1156
	s_mov_b64 s[66:67], exec
	v_lshl_add_u64 v[0:1], v[2:3], 0, v[154:155]
	v_lshlrev_b64 v[0:1], 12, v[0:1]
	v_lshl_add_u64 v[4:5], v[166:167], 0, v[0:1]
	global_load_dwordx4 v[186:189], v[4:5], off
	global_load_dwordx4 v[226:229], v[4:5], off offset:16
	s_branch .LBB0_1157

; __device__ __forceinline__ u32x4 pack8(f32x4 a, f32x4 b) { u32x4 w; w.x = cvtpk(a[0], a[1]); w.y = cvtpk(a[2], a[3]); w.z = cvtpk(b[0], b[1]); w.w = cvtpk(b[2], b[3]); return w; }
; __device__ __forceinline__ void lru_load_rows(const Params& P, int l, int tile, int r0, int c0, u32x4 (&xr)[2][4]) {
;     ...
;             if (pos - i >= 0) v = *(const u32x4*)(XR + (size_t)(m - i) * 1024 + c0);
;             else if (samp) { const float* buf = P.in[I_SC] + ((size_t)((l * 128 + ((m - NPT) >> 2)) * 3) + (3 + pos - i)) * 1024 + c0; v = pack8(*(const f32x4*)buf, *(const f32x4*)(buf + 4)); }
;             xr[j][i] = v;
; template <int MODE> __device__ __forceinline__ void lru_phase(const Params& P, LAS unsigned char* lds, int l, int tid_in) {
;     ...
;             if (tile + tstride < NTILE64) lru_load_rows(P, l, tile + tstride, r0, c0, xr);
; #pragma unroll
;             for (int j = 0; j < 2; ++j) gw[j] = *(const u32x4*)(GG + (size_t)(t0 + r0 + 32 * j) * 1024 + c0);
.LBB0_1157:
	s_or_b64 exec, exec, s[0:1]
	s_or_b64 s[76:77], s[60:61], s[62:63]
	s_or_b64 s[76:77], s[76:77], s[66:67]
	s_cmp_eq_u64 s[76:77], 0
	s_cbranch_scc1 .Lpf_samp_doneb
	s_mov_b64 s[74:75], exec
	s_waitcnt vmcnt(0)
	s_mov_b64 exec, s[60:61]
	v_cvt_pk_bf16_f32 v140, v20, v21
	v_cvt_pk_bf16_f32 v141, v22, v23
	v_cvt_pk_bf16_f32 v142, v24, v25
	v_cvt_pk_bf16_f32 v143, v26, v27
	s_mov_b64 exec, s[62:63]
	v_cvt_pk_bf16_f32 v144, v28, v29
	v_cvt_pk_bf16_f32 v145, v30, v31
	v_cvt_pk_bf16_f32 v146, v82, v83
	v_cvt_pk_bf16_f32 v147, v84, v85
	s_mov_b64 exec, s[66:67]
	v_cvt_pk_bf16_f32 v148, v186, v187
	v_cvt_pk_bf16_f32 v149, v188, v189
	v_cvt_pk_bf16_f32 v150, v226, v227
	v_cvt_pk_bf16_f32 v151, v228, v229
	s_mov_b64 exec, s[74:75]
.Lpf_samp_doneb:
.LBB0_1158:
	v_add_u32_e32 v0, s43, v177
	v_ashrrev_i32_e32 v1, 31, v0
	v_lshlrev_b64 v[0:1], 11, v[0:1]
	v_lshl_add_u64 v[0:1], v[164:165], 0, v[0:1]
	v_add_co_u32_e32 v2, vcc, 0x10000, v0
	s_nop 1
	v_addc_co_u32_e32 v3, vcc, 0, v1, vcc
	global_load_dwordx4 v[40:43], v[0:1], off
	global_load_dwordx4 v[44:47], v[2:3], off
